# GEMM K-loops: the back-edge SALU (pointer bumps, exit compare) moved above the closing barrier of each iteration (loop-edge edit), all four instances
# baseline (speedup 1.0000x reference)
.LBB0_47:
	s_add_i32 s56, s26, 2
	s_add_u32 s57, s0, 0x80
	s_addc_u32 s27, s1, 0
	s_add_i32 s60, 16, 0x10000
	s_cmp_eq_u32 s49, s26
	s_cselect_b32 s27, s21, s27
	s_cselect_b32 s26, s20, s57
	v_add_u32_e32 v154, s60, v137
	s_cselect_b32 s59, s25, s29
	s_cselect_b32 s58, s24, s28
	s_add_i32 s57, 16, 0x14000
	ds_read_b128 v[150:153], v154
	ds_read_b128 v[158:161], v154 offset:1024
	ds_read_b128 v[162:165], v154 offset:2048
	ds_read_b128 v[166:169], v154 offset:3072
	v_add_u32_e32 v154, s57, v137
	ds_read_b128 v[170:173], v154
	ds_read_b128 v[174:177], v154 offset:1024
	ds_read_b128 v[178:181], v154 offset:2048
	ds_read_b128 v[182:185], v154 offset:3072
	v_lshl_add_u64 v[154:155], s[0:1], 0, v[146:147]
	s_add_i32 m0, s38, 0xc000
	ds_read_b128 v[186:189], v157
	ds_read_b128 v[190:193], v157 offset:1024
	ds_read_b128 v[194:197], v157 offset:2048
	ds_read_b128 v[220:223], v157 offset:3072
	ds_read_b128 v[224:227], v157 offset:4096
	ds_read_b128 v[228:231], v157 offset:5120
	ds_read_b128 v[232:235], v157 offset:6144
	ds_read_b128 v[236:239], v157 offset:7168
	global_load_lds_dwordx4 v[154:155], off
	v_lshl_add_u64 v[154:155], s[0:1], 0, v[148:149]
	s_add_i32 m0, s38, 0xe000
	s_nop 0
	global_load_lds_dwordx4 v[154:155], off
	s_waitcnt vmcnt(8)
	s_waitcnt lgkmcnt(0)
	s_barrier
	s_setprio 1
	s_waitcnt lgkmcnt(0)
	v_mfma_f32_16x16x32_bf16 v[120:123], v[150:153], v[186:189], v[120:123]
	v_mfma_f32_16x16x32_bf16 v[124:127], v[162:165], v[186:189], v[124:127]
	v_mfma_f32_16x16x32_bf16 v[108:111], v[150:153], v[194:197], v[108:111]
	v_mfma_f32_16x16x32_bf16 v[104:107], v[162:165], v[194:197], v[104:107]
	v_mfma_f32_16x16x32_bf16 v[92:95], v[150:153], v[224:227], v[92:95]
	v_mfma_f32_16x16x32_bf16 v[88:91], v[162:165], v[224:227], v[88:91]
	v_mfma_f32_16x16x32_bf16 v[76:79], v[150:153], v[232:235], v[76:79]
	v_mfma_f32_16x16x32_bf16 v[72:75], v[162:165], v[232:235], v[72:75]
	v_mfma_f32_16x16x32_bf16 v[120:123], v[158:161], v[190:193], v[120:123]
	v_mfma_f32_16x16x32_bf16 v[124:127], v[166:169], v[190:193], v[124:127]
	v_mfma_f32_16x16x32_bf16 v[108:111], v[158:161], v[220:223], v[108:111]
	v_mfma_f32_16x16x32_bf16 v[104:107], v[166:169], v[220:223], v[104:107]
	v_mfma_f32_16x16x32_bf16 v[92:95], v[158:161], v[228:231], v[92:95]
	v_mfma_f32_16x16x32_bf16 v[88:91], v[166:169], v[228:231], v[88:91]
	v_mfma_f32_16x16x32_bf16 v[76:79], v[158:161], v[236:239], v[76:79]
	v_mfma_f32_16x16x32_bf16 v[72:75], v[166:169], v[236:239], v[72:75]
	s_setprio 0
	s_setprio 1
	v_mfma_f32_16x16x32_bf16 v[116:119], v[170:173], v[186:189], v[116:119]
	v_mfma_f32_16x16x32_bf16 v[112:115], v[178:181], v[186:189], v[112:115]
	v_mfma_f32_16x16x32_bf16 v[100:103], v[170:173], v[194:197], v[100:103]
	v_mfma_f32_16x16x32_bf16 v[96:99], v[178:181], v[194:197], v[96:99]
	v_mfma_f32_16x16x32_bf16 v[84:87], v[170:173], v[224:227], v[84:87]
	v_mfma_f32_16x16x32_bf16 v[80:83], v[178:181], v[224:227], v[80:83]
	v_mfma_f32_16x16x32_bf16 v[68:71], v[170:173], v[232:235], v[68:71]
	v_mfma_f32_16x16x32_bf16 v[64:67], v[178:181], v[232:235], v[64:67]
	v_mfma_f32_16x16x32_bf16 v[116:119], v[174:177], v[190:193], v[116:119]
	v_mfma_f32_16x16x32_bf16 v[112:115], v[182:185], v[190:193], v[112:115]
	v_mfma_f32_16x16x32_bf16 v[100:103], v[174:177], v[220:223], v[100:103]
	v_mfma_f32_16x16x32_bf16 v[96:99], v[182:185], v[220:223], v[96:99]
	v_mfma_f32_16x16x32_bf16 v[84:87], v[174:177], v[228:231], v[84:87]
	v_mfma_f32_16x16x32_bf16 v[80:83], v[182:185], v[228:231], v[80:83]
	v_mfma_f32_16x16x32_bf16 v[68:71], v[174:177], v[236:239], v[68:71]
	v_mfma_f32_16x16x32_bf16 v[64:67], v[182:185], v[236:239], v[64:67]
	s_setprio 0
	s_barrier
	s_add_i32 s60, s60, s35
	v_lshl_add_u64 v[154:155], s[58:59], 0, v[128:129]
	s_mov_b32 m0, s60
	ds_read_b128 v[186:189], v157 offset:16384
	ds_read_b128 v[190:193], v157 offset:17408
	ds_read_b128 v[194:197], v157 offset:18432
	ds_read_b128 v[220:223], v157 offset:19456
	ds_read_b128 v[224:227], v157 offset:20480
	ds_read_b128 v[228:231], v157 offset:21504
	ds_read_b128 v[232:235], v157 offset:22528
	ds_read_b128 v[236:239], v157 offset:23552
	global_load_lds_dwordx4 v[154:155], off
	s_add_i32 m0, s60, 0x2000
	v_lshl_add_u64 v[198:199], s[58:59], 0, v[140:141]
	s_add_u32 s58, s58, s2
	s_addc_u32 s59, s59, s3
	s_add_i32 s57, s57, s35
	global_load_lds_dwordx4 v[198:199], off
	v_lshl_add_u64 v[208:209], s[58:59], 0, v[128:129]
	s_mov_b32 m0, s57
	v_lshl_add_u64 v[244:245], s[58:59], 0, v[140:141]
	global_load_lds_dwordx4 v[208:209], off
	s_add_i32 m0, s57, 0x2000
	v_lshl_add_u64 v[246:247], s[26:27], 0, v[144:145]
	global_load_lds_dwordx4 v[244:245], off
	s_mov_b32 m0, s38
	v_lshl_add_u64 v[248:249], s[26:27], 0, v[142:143]
	global_load_lds_dwordx4 v[246:247], off
	s_mov_b32 m0, s39
	s_nop 0
	global_load_lds_dwordx4 v[248:249], off
	s_waitcnt vmcnt(8)
	s_waitcnt lgkmcnt(0)
	s_barrier
	s_setprio 1
	s_waitcnt lgkmcnt(0)
	v_mfma_f32_16x16x32_bf16 v[60:63], v[150:153], v[186:189], v[60:63]
	v_mfma_f32_16x16x32_bf16 v[56:59], v[162:165], v[186:189], v[56:59]
	v_mfma_f32_16x16x32_bf16 v[44:47], v[150:153], v[194:197], v[44:47]
	v_mfma_f32_16x16x32_bf16 v[40:43], v[162:165], v[194:197], v[40:43]
	v_mfma_f32_16x16x32_bf16 v[28:31], v[150:153], v[224:227], v[28:31]
	v_mfma_f32_16x16x32_bf16 v[24:27], v[162:165], v[224:227], v[24:27]
	v_mfma_f32_16x16x32_bf16 v[12:15], v[150:153], v[232:235], v[12:15]
	v_mfma_f32_16x16x32_bf16 v[8:11], v[162:165], v[232:235], v[8:11]
	v_mfma_f32_16x16x32_bf16 v[60:63], v[158:161], v[190:193], v[60:63]
	v_mfma_f32_16x16x32_bf16 v[56:59], v[166:169], v[190:193], v[56:59]
	v_mfma_f32_16x16x32_bf16 v[44:47], v[158:161], v[220:223], v[44:47]
	v_mfma_f32_16x16x32_bf16 v[40:43], v[166:169], v[220:223], v[40:43]
	v_mfma_f32_16x16x32_bf16 v[28:31], v[158:161], v[228:231], v[28:31]
	v_mfma_f32_16x16x32_bf16 v[24:27], v[166:169], v[228:231], v[24:27]
	v_mfma_f32_16x16x32_bf16 v[12:15], v[158:161], v[236:239], v[12:15]
	v_mfma_f32_16x16x32_bf16 v[8:11], v[166:169], v[236:239], v[8:11]
	s_setprio 0
	s_setprio 1
	v_mfma_f32_16x16x32_bf16 v[52:55], v[170:173], v[186:189], v[52:55]
	v_mfma_f32_16x16x32_bf16 v[48:51], v[178:181], v[186:189], v[48:51]
	v_mfma_f32_16x16x32_bf16 v[36:39], v[170:173], v[194:197], v[36:39]
	v_mfma_f32_16x16x32_bf16 v[32:35], v[178:181], v[194:197], v[32:35]
	v_mfma_f32_16x16x32_bf16 v[20:23], v[170:173], v[224:227], v[20:23]
	v_mfma_f32_16x16x32_bf16 v[16:19], v[178:181], v[224:227], v[16:19]
	v_mfma_f32_16x16x32_bf16 v[4:7], v[170:173], v[232:235], v[4:7]
	v_mfma_f32_16x16x32_bf16 v[0:3], v[178:181], v[232:235], v[0:3]
	v_mfma_f32_16x16x32_bf16 v[52:55], v[174:177], v[190:193], v[52:55]
	v_mfma_f32_16x16x32_bf16 v[48:51], v[182:185], v[190:193], v[48:51]
	v_mfma_f32_16x16x32_bf16 v[36:39], v[174:177], v[220:223], v[36:39]
	v_mfma_f32_16x16x32_bf16 v[32:35], v[182:185], v[220:223], v[32:35]
	v_mfma_f32_16x16x32_bf16 v[20:23], v[174:177], v[228:231], v[20:23]
	v_mfma_f32_16x16x32_bf16 v[16:19], v[182:185], v[228:231], v[16:19]
	v_mfma_f32_16x16x32_bf16 v[4:7], v[174:177], v[236:239], v[4:7]
	v_mfma_f32_16x16x32_bf16 v[0:3], v[182:185], v[236:239], v[0:3]
	s_setprio 0
	s_barrier
	s_add_i32 s57, 16, 0x18000
	s_add_i32 s58, 16, 0x1c000
	v_add_u32_e32 v166, s57, v137
	v_add_u32_e32 v182, s58, v137
	ds_read_b128 v[150:153], v166
	ds_read_b128 v[158:161], v166 offset:1024
	ds_read_b128 v[162:165], v166 offset:2048
	ds_read_b128 v[166:169], v166 offset:3072
	ds_read_b128 v[170:173], v182
	ds_read_b128 v[174:177], v182 offset:1024
	ds_read_b128 v[178:181], v182 offset:2048
	ds_read_b128 v[182:185], v182 offset:3072
	s_add_u32 s26, s26, s2
	s_addc_u32 s27, s27, s3
	s_mov_b32 m0, s44
	v_lshl_add_u64 v[250:251], s[26:27], 0, v[144:145]
	ds_read_b128 v[186:189], v157 offset:32768
	ds_read_b128 v[190:193], v157 offset:33792
	ds_read_b128 v[194:197], v157 offset:34816
	ds_read_b128 v[220:223], v157 offset:35840
	ds_read_b128 v[224:227], v157 offset:36864
	ds_read_b128 v[228:231], v157 offset:37888
	ds_read_b128 v[232:235], v157 offset:38912
	ds_read_b128 v[236:239], v157 offset:39936
	global_load_lds_dwordx4 v[250:251], off
	v_lshl_add_u64 v[250:251], s[26:27], 0, v[142:143]
	s_mov_b32 m0, s45
	s_nop 0
	global_load_lds_dwordx4 v[250:251], off
	s_waitcnt vmcnt(8)
	s_waitcnt lgkmcnt(0)
	s_barrier
	s_setprio 1
	s_waitcnt lgkmcnt(0)
	v_mfma_f32_16x16x32_bf16 v[120:123], v[150:153], v[186:189], v[120:123]
	v_mfma_f32_16x16x32_bf16 v[124:127], v[162:165], v[186:189], v[124:127]
	v_mfma_f32_16x16x32_bf16 v[108:111], v[150:153], v[194:197], v[108:111]
	v_mfma_f32_16x16x32_bf16 v[104:107], v[162:165], v[194:197], v[104:107]
	v_mfma_f32_16x16x32_bf16 v[92:95], v[150:153], v[224:227], v[92:95]
	v_mfma_f32_16x16x32_bf16 v[88:91], v[162:165], v[224:227], v[88:91]
	v_mfma_f32_16x16x32_bf16 v[76:79], v[150:153], v[232:235], v[76:79]
	v_mfma_f32_16x16x32_bf16 v[72:75], v[162:165], v[232:235], v[72:75]
	v_mfma_f32_16x16x32_bf16 v[120:123], v[158:161], v[190:193], v[120:123]
	v_mfma_f32_16x16x32_bf16 v[124:127], v[166:169], v[190:193], v[124:127]
	v_mfma_f32_16x16x32_bf16 v[108:111], v[158:161], v[220:223], v[108:111]
	v_mfma_f32_16x16x32_bf16 v[104:107], v[166:169], v[220:223], v[104:107]
	v_mfma_f32_16x16x32_bf16 v[92:95], v[158:161], v[228:231], v[92:95]
	v_mfma_f32_16x16x32_bf16 v[88:91], v[166:169], v[228:231], v[88:91]
	v_mfma_f32_16x16x32_bf16 v[76:79], v[158:161], v[236:239], v[76:79]
	v_mfma_f32_16x16x32_bf16 v[72:75], v[166:169], v[236:239], v[72:75]
	s_setprio 0
	s_setprio 1
	v_mfma_f32_16x16x32_bf16 v[116:119], v[170:173], v[186:189], v[116:119]
	v_mfma_f32_16x16x32_bf16 v[112:115], v[178:181], v[186:189], v[112:115]
	v_mfma_f32_16x16x32_bf16 v[100:103], v[170:173], v[194:197], v[100:103]
	v_mfma_f32_16x16x32_bf16 v[96:99], v[178:181], v[194:197], v[96:99]
	v_mfma_f32_16x16x32_bf16 v[84:87], v[170:173], v[224:227], v[84:87]
	v_mfma_f32_16x16x32_bf16 v[80:83], v[178:181], v[224:227], v[80:83]
	v_mfma_f32_16x16x32_bf16 v[68:71], v[170:173], v[232:235], v[68:71]
	v_mfma_f32_16x16x32_bf16 v[64:67], v[178:181], v[232:235], v[64:67]
	v_mfma_f32_16x16x32_bf16 v[116:119], v[174:177], v[190:193], v[116:119]
	v_mfma_f32_16x16x32_bf16 v[112:115], v[182:185], v[190:193], v[112:115]
	v_mfma_f32_16x16x32_bf16 v[100:103], v[174:177], v[220:223], v[100:103]
	v_mfma_f32_16x16x32_bf16 v[96:99], v[182:185], v[220:223], v[96:99]
	v_mfma_f32_16x16x32_bf16 v[84:87], v[174:177], v[228:231], v[84:87]
	v_mfma_f32_16x16x32_bf16 v[80:83], v[182:185], v[228:231], v[80:83]
	v_mfma_f32_16x16x32_bf16 v[68:71], v[174:177], v[236:239], v[68:71]
	v_mfma_f32_16x16x32_bf16 v[64:67], v[182:185], v[236:239], v[64:67]
	s_setprio 0
	s_barrier
	s_add_i32 s26, s57, s35
	v_lshl_add_u64 v[154:155], v[154:155], 0, s[98:99]
	s_mov_b32 m0, s26
	ds_read_b128 v[186:189], v157 offset:49152
	ds_read_b128 v[190:193], v157 offset:50176
	ds_read_b128 v[194:197], v157 offset:51200
	ds_read_b128 v[220:223], v157 offset:52224
	ds_read_b128 v[224:227], v157 offset:53248
	ds_read_b128 v[228:231], v157 offset:54272
	ds_read_b128 v[232:235], v157 offset:55296
	ds_read_b128 v[236:239], v157 offset:56320
	global_load_lds_dwordx4 v[154:155], off
	v_lshl_add_u64 v[154:155], v[198:199], 0, s[98:99]
	s_add_i32 m0, s26, 0x2000
	s_add_i32 s26, s58, s35
	global_load_lds_dwordx4 v[154:155], off
	v_lshl_add_u64 v[154:155], v[208:209], 0, s[98:99]
	s_mov_b32 m0, s26
	s_nop 0
	global_load_lds_dwordx4 v[154:155], off
	v_lshl_add_u64 v[154:155], v[244:245], 0, s[98:99]
	s_add_i32 m0, s26, 0x2000
	s_nop 0
	global_load_lds_dwordx4 v[154:155], off
	v_lshl_add_u64 v[154:155], v[246:247], 0, s[98:99]
	s_mov_b32 m0, s46
	s_nop 0
	global_load_lds_dwordx4 v[154:155], off
	v_lshl_add_u64 v[154:155], v[248:249], 0, s[98:99]
	s_mov_b32 m0, s47
	s_nop 0
	global_load_lds_dwordx4 v[154:155], off
	s_waitcnt vmcnt(8)
	s_waitcnt lgkmcnt(0)
	s_barrier
	s_setprio 1
	s_waitcnt lgkmcnt(0)
	v_mfma_f32_16x16x32_bf16 v[60:63], v[150:153], v[186:189], v[60:63]
	v_mfma_f32_16x16x32_bf16 v[56:59], v[162:165], v[186:189], v[56:59]
	v_mfma_f32_16x16x32_bf16 v[44:47], v[150:153], v[194:197], v[44:47]
	v_mfma_f32_16x16x32_bf16 v[40:43], v[162:165], v[194:197], v[40:43]
	v_mfma_f32_16x16x32_bf16 v[28:31], v[150:153], v[224:227], v[28:31]
	v_mfma_f32_16x16x32_bf16 v[24:27], v[162:165], v[224:227], v[24:27]
	v_mfma_f32_16x16x32_bf16 v[12:15], v[150:153], v[232:235], v[12:15]
	v_mfma_f32_16x16x32_bf16 v[8:11], v[162:165], v[232:235], v[8:11]
	v_mfma_f32_16x16x32_bf16 v[60:63], v[158:161], v[190:193], v[60:63]
	v_mfma_f32_16x16x32_bf16 v[56:59], v[166:169], v[190:193], v[56:59]
	v_mfma_f32_16x16x32_bf16 v[44:47], v[158:161], v[220:223], v[44:47]
	v_mfma_f32_16x16x32_bf16 v[40:43], v[166:169], v[220:223], v[40:43]
	v_mfma_f32_16x16x32_bf16 v[28:31], v[158:161], v[228:231], v[28:31]
	v_mfma_f32_16x16x32_bf16 v[24:27], v[166:169], v[228:231], v[24:27]
	v_mfma_f32_16x16x32_bf16 v[12:15], v[158:161], v[236:239], v[12:15]
	v_mfma_f32_16x16x32_bf16 v[8:11], v[166:169], v[236:239], v[8:11]
	s_setprio 0
	s_setprio 1
	v_mfma_f32_16x16x32_bf16 v[52:55], v[170:173], v[186:189], v[52:55]
	v_mfma_f32_16x16x32_bf16 v[48:51], v[178:181], v[186:189], v[48:51]
	v_mfma_f32_16x16x32_bf16 v[36:39], v[170:173], v[194:197], v[36:39]
	v_mfma_f32_16x16x32_bf16 v[32:35], v[178:181], v[194:197], v[32:35]
	v_mfma_f32_16x16x32_bf16 v[20:23], v[170:173], v[224:227], v[20:23]
	v_mfma_f32_16x16x32_bf16 v[16:19], v[178:181], v[224:227], v[16:19]
	v_mfma_f32_16x16x32_bf16 v[4:7], v[170:173], v[232:235], v[4:7]
	v_mfma_f32_16x16x32_bf16 v[0:3], v[178:181], v[232:235], v[0:3]
	v_mfma_f32_16x16x32_bf16 v[52:55], v[174:177], v[190:193], v[52:55]
	v_mfma_f32_16x16x32_bf16 v[48:51], v[182:185], v[190:193], v[48:51]
	v_mfma_f32_16x16x32_bf16 v[36:39], v[174:177], v[220:223], v[36:39]
	v_mfma_f32_16x16x32_bf16 v[32:35], v[182:185], v[220:223], v[32:35]
	v_mfma_f32_16x16x32_bf16 v[20:23], v[174:177], v[228:231], v[20:23]
	v_mfma_f32_16x16x32_bf16 v[16:19], v[182:185], v[228:231], v[16:19]
	v_mfma_f32_16x16x32_bf16 v[4:7], v[174:177], v[236:239], v[4:7]
	v_mfma_f32_16x16x32_bf16 v[0:3], v[182:185], v[236:239], v[0:3]
	s_setprio 0
	s_add_u32 s0, s0, 0x100
	s_addc_u32 s1, s1, 0
	s_add_u32 s28, s28, 0x100
	s_addc_u32 s29, s29, 0
	s_cmp_ge_i32 s56, s48
	s_mov_b32 s26, s56
	s_barrier
	s_cbranch_scc0 .LBB0_47
	v_readlane_b32 s58, v255, 20
	v_readlane_b32 s59, v255, 21
	s_mov_b32 s60, 0xec801000

.LBB0_103:
	s_add_i32 s56, s26, 2
	s_add_u32 s57, s24, 0x80
	s_addc_u32 s27, s25, 0
	s_add_i32 s60, 16, 0x10000
	s_cmp_eq_u32 s47, s26
	s_cselect_b32 s27, s1, s27
	s_cselect_b32 s26, s0, s57
	v_add_u32_e32 v150, s60, v137
	s_cselect_b32 s59, s21, s55
	s_cselect_b32 s58, s20, s54
	s_add_i32 s57, 16, 0x14000
	ds_read_b128 v[154:157], v150
	ds_read_b128 v[158:161], v150 offset:1024
	ds_read_b128 v[162:165], v150 offset:2048
	ds_read_b128 v[166:169], v150 offset:3072
	v_add_u32_e32 v150, s57, v137
	ds_read_b128 v[170:173], v150
	ds_read_b128 v[174:177], v150 offset:1024
	ds_read_b128 v[178:181], v150 offset:2048
	ds_read_b128 v[182:185], v150 offset:3072
	v_lshl_add_u64 v[150:151], s[24:25], 0, v[146:147]
	s_add_i32 m0, s36, 0xc000
	ds_read_b128 v[186:189], v153
	ds_read_b128 v[190:193], v153 offset:1024
	ds_read_b128 v[194:197], v153 offset:2048
	ds_read_b128 v[220:223], v153 offset:3072
	ds_read_b128 v[224:227], v153 offset:4096
	ds_read_b128 v[228:231], v153 offset:5120
	ds_read_b128 v[232:235], v153 offset:6144
	ds_read_b128 v[236:239], v153 offset:7168
	global_load_lds_dwordx4 v[150:151], off
	v_lshl_add_u64 v[150:151], s[24:25], 0, v[148:149]
	s_add_i32 m0, s36, 0xe000
	s_nop 0
	global_load_lds_dwordx4 v[150:151], off
	s_waitcnt vmcnt(8)
	s_waitcnt lgkmcnt(0)
	s_barrier
	s_setprio 1
	s_waitcnt lgkmcnt(0)
	v_mfma_f32_16x16x32_bf16 v[124:127], v[154:157], v[186:189], v[124:127]
	v_mfma_f32_16x16x32_bf16 v[116:119], v[162:165], v[186:189], v[116:119]
	v_mfma_f32_16x16x32_bf16 v[108:111], v[154:157], v[194:197], v[108:111]
	v_mfma_f32_16x16x32_bf16 v[100:103], v[162:165], v[194:197], v[100:103]
	v_mfma_f32_16x16x32_bf16 v[92:95], v[154:157], v[224:227], v[92:95]
	v_mfma_f32_16x16x32_bf16 v[84:87], v[162:165], v[224:227], v[84:87]
	v_mfma_f32_16x16x32_bf16 v[76:79], v[154:157], v[232:235], v[76:79]
	v_mfma_f32_16x16x32_bf16 v[68:71], v[162:165], v[232:235], v[68:71]
	v_mfma_f32_16x16x32_bf16 v[124:127], v[158:161], v[190:193], v[124:127]
	v_mfma_f32_16x16x32_bf16 v[116:119], v[166:169], v[190:193], v[116:119]
	v_mfma_f32_16x16x32_bf16 v[108:111], v[158:161], v[220:223], v[108:111]
	v_mfma_f32_16x16x32_bf16 v[100:103], v[166:169], v[220:223], v[100:103]
	v_mfma_f32_16x16x32_bf16 v[92:95], v[158:161], v[228:231], v[92:95]
	v_mfma_f32_16x16x32_bf16 v[84:87], v[166:169], v[228:231], v[84:87]
	v_mfma_f32_16x16x32_bf16 v[76:79], v[158:161], v[236:239], v[76:79]
	v_mfma_f32_16x16x32_bf16 v[68:71], v[166:169], v[236:239], v[68:71]
	s_setprio 0
	s_setprio 1
	v_mfma_f32_16x16x32_bf16 v[120:123], v[170:173], v[186:189], v[120:123]
	v_mfma_f32_16x16x32_bf16 v[112:115], v[178:181], v[186:189], v[112:115]
	v_mfma_f32_16x16x32_bf16 v[104:107], v[170:173], v[194:197], v[104:107]
	v_mfma_f32_16x16x32_bf16 v[96:99], v[178:181], v[194:197], v[96:99]
	v_mfma_f32_16x16x32_bf16 v[88:91], v[170:173], v[224:227], v[88:91]
	v_mfma_f32_16x16x32_bf16 v[80:83], v[178:181], v[224:227], v[80:83]
	v_mfma_f32_16x16x32_bf16 v[72:75], v[170:173], v[232:235], v[72:75]
	v_mfma_f32_16x16x32_bf16 v[64:67], v[178:181], v[232:235], v[64:67]
	v_mfma_f32_16x16x32_bf16 v[120:123], v[174:177], v[190:193], v[120:123]
	v_mfma_f32_16x16x32_bf16 v[112:115], v[182:185], v[190:193], v[112:115]
	v_mfma_f32_16x16x32_bf16 v[104:107], v[174:177], v[220:223], v[104:107]
	v_mfma_f32_16x16x32_bf16 v[96:99], v[182:185], v[220:223], v[96:99]
	v_mfma_f32_16x16x32_bf16 v[88:91], v[174:177], v[228:231], v[88:91]
	v_mfma_f32_16x16x32_bf16 v[80:83], v[182:185], v[228:231], v[80:83]
	v_mfma_f32_16x16x32_bf16 v[72:75], v[174:177], v[236:239], v[72:75]
	v_mfma_f32_16x16x32_bf16 v[64:67], v[182:185], v[236:239], v[64:67]
	s_setprio 0
	s_barrier
	s_add_i32 s60, s60, s29
	v_lshl_add_u64 v[150:151], s[58:59], 0, v[128:129]
	s_mov_b32 m0, s60
	ds_read_b128 v[186:189], v153 offset:16384
	ds_read_b128 v[190:193], v153 offset:17408
	ds_read_b128 v[194:197], v153 offset:18432
	ds_read_b128 v[220:223], v153 offset:19456
	ds_read_b128 v[224:227], v153 offset:20480
	ds_read_b128 v[228:231], v153 offset:21504
	ds_read_b128 v[232:235], v153 offset:22528
	ds_read_b128 v[236:239], v153 offset:23552
	global_load_lds_dwordx4 v[150:151], off
	s_add_i32 m0, s60, 0x2000
	v_lshl_add_u64 v[198:199], s[58:59], 0, v[140:141]
	s_add_u32 s58, s58, s2
	s_addc_u32 s59, s59, s3
	s_add_i32 s57, s57, s29
	global_load_lds_dwordx4 v[198:199], off
	v_lshl_add_u64 v[208:209], s[58:59], 0, v[128:129]
	s_mov_b32 m0, s57
	v_lshl_add_u64 v[244:245], s[58:59], 0, v[140:141]
	global_load_lds_dwordx4 v[208:209], off
	s_add_i32 m0, s57, 0x2000
	v_lshl_add_u64 v[246:247], s[26:27], 0, v[144:145]
	global_load_lds_dwordx4 v[244:245], off
	s_mov_b32 m0, s36
	v_lshl_add_u64 v[248:249], s[26:27], 0, v[142:143]
	global_load_lds_dwordx4 v[246:247], off
	s_mov_b32 m0, s37
	s_nop 0
	global_load_lds_dwordx4 v[248:249], off
	s_waitcnt vmcnt(8)
	s_waitcnt lgkmcnt(0)
	s_barrier
	s_setprio 1
	s_waitcnt lgkmcnt(0)
	v_mfma_f32_16x16x32_bf16 v[60:63], v[154:157], v[186:189], v[60:63]
	v_mfma_f32_16x16x32_bf16 v[52:55], v[162:165], v[186:189], v[52:55]
	v_mfma_f32_16x16x32_bf16 v[44:47], v[154:157], v[194:197], v[44:47]
	v_mfma_f32_16x16x32_bf16 v[36:39], v[162:165], v[194:197], v[36:39]
	v_mfma_f32_16x16x32_bf16 v[28:31], v[154:157], v[224:227], v[28:31]
	v_mfma_f32_16x16x32_bf16 v[20:23], v[162:165], v[224:227], v[20:23]
	v_mfma_f32_16x16x32_bf16 v[12:15], v[154:157], v[232:235], v[12:15]
	v_mfma_f32_16x16x32_bf16 v[4:7], v[162:165], v[232:235], v[4:7]
	v_mfma_f32_16x16x32_bf16 v[60:63], v[158:161], v[190:193], v[60:63]
	v_mfma_f32_16x16x32_bf16 v[52:55], v[166:169], v[190:193], v[52:55]
	v_mfma_f32_16x16x32_bf16 v[44:47], v[158:161], v[220:223], v[44:47]
	v_mfma_f32_16x16x32_bf16 v[36:39], v[166:169], v[220:223], v[36:39]
	v_mfma_f32_16x16x32_bf16 v[28:31], v[158:161], v[228:231], v[28:31]
	v_mfma_f32_16x16x32_bf16 v[20:23], v[166:169], v[228:231], v[20:23]
	v_mfma_f32_16x16x32_bf16 v[12:15], v[158:161], v[236:239], v[12:15]
	v_mfma_f32_16x16x32_bf16 v[4:7], v[166:169], v[236:239], v[4:7]
	s_setprio 0
	s_setprio 1
	v_mfma_f32_16x16x32_bf16 v[56:59], v[170:173], v[186:189], v[56:59]
	v_mfma_f32_16x16x32_bf16 v[48:51], v[178:181], v[186:189], v[48:51]
	v_mfma_f32_16x16x32_bf16 v[40:43], v[170:173], v[194:197], v[40:43]
	v_mfma_f32_16x16x32_bf16 v[32:35], v[178:181], v[194:197], v[32:35]
	v_mfma_f32_16x16x32_bf16 v[24:27], v[170:173], v[224:227], v[24:27]
	v_mfma_f32_16x16x32_bf16 v[16:19], v[178:181], v[224:227], v[16:19]
	v_mfma_f32_16x16x32_bf16 v[8:11], v[170:173], v[232:235], v[8:11]
	v_mfma_f32_16x16x32_bf16 v[0:3], v[178:181], v[232:235], v[0:3]
	v_mfma_f32_16x16x32_bf16 v[56:59], v[174:177], v[190:193], v[56:59]
	v_mfma_f32_16x16x32_bf16 v[48:51], v[182:185], v[190:193], v[48:51]
	v_mfma_f32_16x16x32_bf16 v[40:43], v[174:177], v[220:223], v[40:43]
	v_mfma_f32_16x16x32_bf16 v[32:35], v[182:185], v[220:223], v[32:35]
	v_mfma_f32_16x16x32_bf16 v[24:27], v[174:177], v[228:231], v[24:27]
	v_mfma_f32_16x16x32_bf16 v[16:19], v[182:185], v[228:231], v[16:19]
	v_mfma_f32_16x16x32_bf16 v[8:11], v[174:177], v[236:239], v[8:11]
	v_mfma_f32_16x16x32_bf16 v[0:3], v[182:185], v[236:239], v[0:3]
	s_setprio 0
	s_barrier
	s_add_i32 s57, 16, 0x18000
	s_add_i32 s58, 16, 0x1c000
	v_add_u32_e32 v166, s57, v137
	v_add_u32_e32 v182, s58, v137
	ds_read_b128 v[154:157], v166
	ds_read_b128 v[158:161], v166 offset:1024
	ds_read_b128 v[162:165], v166 offset:2048
	ds_read_b128 v[166:169], v166 offset:3072
	ds_read_b128 v[170:173], v182
	ds_read_b128 v[174:177], v182 offset:1024
	ds_read_b128 v[178:181], v182 offset:2048
	ds_read_b128 v[182:185], v182 offset:3072
	s_add_u32 s26, s26, s2
	s_addc_u32 s27, s27, s3
	s_mov_b32 m0, s38
	v_lshl_add_u64 v[250:251], s[26:27], 0, v[144:145]
	ds_read_b128 v[186:189], v153 offset:32768
	ds_read_b128 v[190:193], v153 offset:33792
	ds_read_b128 v[194:197], v153 offset:34816
	ds_read_b128 v[220:223], v153 offset:35840
	ds_read_b128 v[224:227], v153 offset:36864
	ds_read_b128 v[228:231], v153 offset:37888
	ds_read_b128 v[232:235], v153 offset:38912
	ds_read_b128 v[236:239], v153 offset:39936
	global_load_lds_dwordx4 v[250:251], off
	v_lshl_add_u64 v[250:251], s[26:27], 0, v[142:143]
	s_mov_b32 m0, s39
	s_nop 0
	global_load_lds_dwordx4 v[250:251], off
	s_waitcnt vmcnt(8)
	s_waitcnt lgkmcnt(0)
	s_barrier
	s_setprio 1
	s_waitcnt lgkmcnt(0)
	v_mfma_f32_16x16x32_bf16 v[124:127], v[154:157], v[186:189], v[124:127]
	v_mfma_f32_16x16x32_bf16 v[116:119], v[162:165], v[186:189], v[116:119]
	v_mfma_f32_16x16x32_bf16 v[108:111], v[154:157], v[194:197], v[108:111]
	v_mfma_f32_16x16x32_bf16 v[100:103], v[162:165], v[194:197], v[100:103]
	v_mfma_f32_16x16x32_bf16 v[92:95], v[154:157], v[224:227], v[92:95]
	v_mfma_f32_16x16x32_bf16 v[84:87], v[162:165], v[224:227], v[84:87]
	v_mfma_f32_16x16x32_bf16 v[76:79], v[154:157], v[232:235], v[76:79]
	v_mfma_f32_16x16x32_bf16 v[68:71], v[162:165], v[232:235], v[68:71]
	v_mfma_f32_16x16x32_bf16 v[124:127], v[158:161], v[190:193], v[124:127]
	v_mfma_f32_16x16x32_bf16 v[116:119], v[166:169], v[190:193], v[116:119]
	v_mfma_f32_16x16x32_bf16 v[108:111], v[158:161], v[220:223], v[108:111]
	v_mfma_f32_16x16x32_bf16 v[100:103], v[166:169], v[220:223], v[100:103]
	v_mfma_f32_16x16x32_bf16 v[92:95], v[158:161], v[228:231], v[92:95]
	v_mfma_f32_16x16x32_bf16 v[84:87], v[166:169], v[228:231], v[84:87]
	v_mfma_f32_16x16x32_bf16 v[76:79], v[158:161], v[236:239], v[76:79]
	v_mfma_f32_16x16x32_bf16 v[68:71], v[166:169], v[236:239], v[68:71]
	s_setprio 0
	s_setprio 1
	v_mfma_f32_16x16x32_bf16 v[120:123], v[170:173], v[186:189], v[120:123]
	v_mfma_f32_16x16x32_bf16 v[112:115], v[178:181], v[186:189], v[112:115]
	v_mfma_f32_16x16x32_bf16 v[104:107], v[170:173], v[194:197], v[104:107]
	v_mfma_f32_16x16x32_bf16 v[96:99], v[178:181], v[194:197], v[96:99]
	v_mfma_f32_16x16x32_bf16 v[88:91], v[170:173], v[224:227], v[88:91]
	v_mfma_f32_16x16x32_bf16 v[80:83], v[178:181], v[224:227], v[80:83]
	v_mfma_f32_16x16x32_bf16 v[72:75], v[170:173], v[232:235], v[72:75]
	v_mfma_f32_16x16x32_bf16 v[64:67], v[178:181], v[232:235], v[64:67]
	v_mfma_f32_16x16x32_bf16 v[120:123], v[174:177], v[190:193], v[120:123]
	v_mfma_f32_16x16x32_bf16 v[112:115], v[182:185], v[190:193], v[112:115]
	v_mfma_f32_16x16x32_bf16 v[104:107], v[174:177], v[220:223], v[104:107]
	v_mfma_f32_16x16x32_bf16 v[96:99], v[182:185], v[220:223], v[96:99]
	v_mfma_f32_16x16x32_bf16 v[88:91], v[174:177], v[228:231], v[88:91]
	v_mfma_f32_16x16x32_bf16 v[80:83], v[182:185], v[228:231], v[80:83]
	v_mfma_f32_16x16x32_bf16 v[72:75], v[174:177], v[236:239], v[72:75]
	v_mfma_f32_16x16x32_bf16 v[64:67], v[182:185], v[236:239], v[64:67]
	s_setprio 0
	s_barrier
	s_add_i32 s26, s57, s29
	v_lshl_add_u64 v[150:151], v[150:151], 0, s[98:99]
	s_mov_b32 m0, s26
	ds_read_b128 v[186:189], v153 offset:49152
	ds_read_b128 v[190:193], v153 offset:50176
	ds_read_b128 v[194:197], v153 offset:51200
	ds_read_b128 v[220:223], v153 offset:52224
	ds_read_b128 v[224:227], v153 offset:53248
	ds_read_b128 v[228:231], v153 offset:54272
	ds_read_b128 v[232:235], v153 offset:55296
	ds_read_b128 v[236:239], v153 offset:56320
	global_load_lds_dwordx4 v[150:151], off
	v_lshl_add_u64 v[150:151], v[198:199], 0, s[98:99]
	s_add_i32 m0, s26, 0x2000
	s_add_i32 s26, s58, s29
	global_load_lds_dwordx4 v[150:151], off
	v_lshl_add_u64 v[150:151], v[208:209], 0, s[98:99]
	s_mov_b32 m0, s26
	s_nop 0
	global_load_lds_dwordx4 v[150:151], off
	v_lshl_add_u64 v[150:151], v[244:245], 0, s[98:99]
	s_add_i32 m0, s26, 0x2000
	s_nop 0
	global_load_lds_dwordx4 v[150:151], off
	v_lshl_add_u64 v[150:151], v[246:247], 0, s[98:99]
	s_mov_b32 m0, s44
	s_nop 0
	global_load_lds_dwordx4 v[150:151], off
	v_lshl_add_u64 v[150:151], v[248:249], 0, s[98:99]
	s_mov_b32 m0, s45
	s_nop 0
	global_load_lds_dwordx4 v[150:151], off
	s_waitcnt vmcnt(8)
	s_waitcnt lgkmcnt(0)
	s_barrier
	s_setprio 1
	s_waitcnt lgkmcnt(0)
	v_mfma_f32_16x16x32_bf16 v[60:63], v[154:157], v[186:189], v[60:63]
	v_mfma_f32_16x16x32_bf16 v[52:55], v[162:165], v[186:189], v[52:55]
	v_mfma_f32_16x16x32_bf16 v[44:47], v[154:157], v[194:197], v[44:47]
	v_mfma_f32_16x16x32_bf16 v[36:39], v[162:165], v[194:197], v[36:39]
	v_mfma_f32_16x16x32_bf16 v[28:31], v[154:157], v[224:227], v[28:31]
	v_mfma_f32_16x16x32_bf16 v[20:23], v[162:165], v[224:227], v[20:23]
	v_mfma_f32_16x16x32_bf16 v[12:15], v[154:157], v[232:235], v[12:15]
	v_mfma_f32_16x16x32_bf16 v[4:7], v[162:165], v[232:235], v[4:7]
	v_mfma_f32_16x16x32_bf16 v[60:63], v[158:161], v[190:193], v[60:63]
	v_mfma_f32_16x16x32_bf16 v[52:55], v[166:169], v[190:193], v[52:55]
	v_mfma_f32_16x16x32_bf16 v[44:47], v[158:161], v[220:223], v[44:47]
	v_mfma_f32_16x16x32_bf16 v[36:39], v[166:169], v[220:223], v[36:39]
	v_mfma_f32_16x16x32_bf16 v[28:31], v[158:161], v[228:231], v[28:31]
	v_mfma_f32_16x16x32_bf16 v[20:23], v[166:169], v[228:231], v[20:23]
	v_mfma_f32_16x16x32_bf16 v[12:15], v[158:161], v[236:239], v[12:15]
	v_mfma_f32_16x16x32_bf16 v[4:7], v[166:169], v[236:239], v[4:7]
	s_setprio 0
	s_setprio 1
	v_mfma_f32_16x16x32_bf16 v[56:59], v[170:173], v[186:189], v[56:59]
	v_mfma_f32_16x16x32_bf16 v[48:51], v[178:181], v[186:189], v[48:51]
	v_mfma_f32_16x16x32_bf16 v[40:43], v[170:173], v[194:197], v[40:43]
	v_mfma_f32_16x16x32_bf16 v[32:35], v[178:181], v[194:197], v[32:35]
	v_mfma_f32_16x16x32_bf16 v[24:27], v[170:173], v[224:227], v[24:27]
	v_mfma_f32_16x16x32_bf16 v[16:19], v[178:181], v[224:227], v[16:19]
	v_mfma_f32_16x16x32_bf16 v[8:11], v[170:173], v[232:235], v[8:11]
	v_mfma_f32_16x16x32_bf16 v[0:3], v[178:181], v[232:235], v[0:3]
	v_mfma_f32_16x16x32_bf16 v[56:59], v[174:177], v[190:193], v[56:59]
	v_mfma_f32_16x16x32_bf16 v[48:51], v[182:185], v[190:193], v[48:51]
	v_mfma_f32_16x16x32_bf16 v[40:43], v[174:177], v[220:223], v[40:43]
	v_mfma_f32_16x16x32_bf16 v[32:35], v[182:185], v[220:223], v[32:35]
	v_mfma_f32_16x16x32_bf16 v[24:27], v[174:177], v[228:231], v[24:27]
	v_mfma_f32_16x16x32_bf16 v[16:19], v[182:185], v[228:231], v[16:19]
	v_mfma_f32_16x16x32_bf16 v[8:11], v[174:177], v[236:239], v[8:11]
	v_mfma_f32_16x16x32_bf16 v[0:3], v[182:185], v[236:239], v[0:3]
	s_setprio 0
	s_add_u32 s24, s24, 0x100
	s_addc_u32 s25, s25, 0
	s_add_u32 s54, s54, 0x100
	s_addc_u32 s55, s55, 0
	s_cmp_ge_i32 s56, s46
	s_mov_b32 s26, s56
	s_barrier
	s_cbranch_scc0 .LBB0_103
	v_readlane_b32 s58, v255, 20
	v_readlane_b32 s59, v255, 21
	s_mov_b32 s60, 0xec801000

.LBB0_139:
	s_add_i32 s54, s26, 2
	s_add_u32 s55, s0, 0x80
	s_addc_u32 s27, s1, 0
	s_add_i32 s58, 16, 0x10000
	s_cmp_eq_u32 s47, s26
	s_cselect_b32 s27, s21, s27
	s_cselect_b32 s26, s20, s55
	v_add_u32_e32 v154, s58, v137
	s_cselect_b32 s57, s25, s29
	s_cselect_b32 s56, s24, s28
	s_add_i32 s55, 16, 0x14000
	ds_read_b128 v[150:153], v154
	ds_read_b128 v[158:161], v154 offset:1024
	ds_read_b128 v[162:165], v154 offset:2048
	ds_read_b128 v[166:169], v154 offset:3072
	v_add_u32_e32 v154, s55, v137
	ds_read_b128 v[170:173], v154
	ds_read_b128 v[174:177], v154 offset:1024
	ds_read_b128 v[178:181], v154 offset:2048
	ds_read_b128 v[182:185], v154 offset:3072
	v_lshl_add_u64 v[154:155], s[0:1], 0, v[146:147]
	s_add_i32 m0, s38, 0xc000
	ds_read_b128 v[186:189], v157
	ds_read_b128 v[190:193], v157 offset:1024
	ds_read_b128 v[194:197], v157 offset:2048
	ds_read_b128 v[220:223], v157 offset:3072
	ds_read_b128 v[224:227], v157 offset:4096
	ds_read_b128 v[228:231], v157 offset:5120
	ds_read_b128 v[232:235], v157 offset:6144
	ds_read_b128 v[236:239], v157 offset:7168
	global_load_lds_dwordx4 v[154:155], off
	v_lshl_add_u64 v[154:155], s[0:1], 0, v[148:149]
	s_add_i32 m0, s38, 0xe000
	s_nop 0
	global_load_lds_dwordx4 v[154:155], off
	s_waitcnt vmcnt(8)
	s_waitcnt lgkmcnt(0)
	s_barrier
	s_setprio 1
	s_waitcnt lgkmcnt(0)
	v_mfma_f32_16x16x32_bf16 v[120:123], v[150:153], v[186:189], v[120:123]
	v_mfma_f32_16x16x32_bf16 v[124:127], v[162:165], v[186:189], v[124:127]
	v_mfma_f32_16x16x32_bf16 v[108:111], v[150:153], v[194:197], v[108:111]
	v_mfma_f32_16x16x32_bf16 v[104:107], v[162:165], v[194:197], v[104:107]
	v_mfma_f32_16x16x32_bf16 v[92:95], v[150:153], v[224:227], v[92:95]
	v_mfma_f32_16x16x32_bf16 v[88:91], v[162:165], v[224:227], v[88:91]
	v_mfma_f32_16x16x32_bf16 v[76:79], v[150:153], v[232:235], v[76:79]
	v_mfma_f32_16x16x32_bf16 v[72:75], v[162:165], v[232:235], v[72:75]
	v_mfma_f32_16x16x32_bf16 v[120:123], v[158:161], v[190:193], v[120:123]
	v_mfma_f32_16x16x32_bf16 v[124:127], v[166:169], v[190:193], v[124:127]
	v_mfma_f32_16x16x32_bf16 v[108:111], v[158:161], v[220:223], v[108:111]
	v_mfma_f32_16x16x32_bf16 v[104:107], v[166:169], v[220:223], v[104:107]
	v_mfma_f32_16x16x32_bf16 v[92:95], v[158:161], v[228:231], v[92:95]
	v_mfma_f32_16x16x32_bf16 v[88:91], v[166:169], v[228:231], v[88:91]
	v_mfma_f32_16x16x32_bf16 v[76:79], v[158:161], v[236:239], v[76:79]
	v_mfma_f32_16x16x32_bf16 v[72:75], v[166:169], v[236:239], v[72:75]
	s_setprio 0
	s_setprio 1
	v_mfma_f32_16x16x32_bf16 v[116:119], v[170:173], v[186:189], v[116:119]
	v_mfma_f32_16x16x32_bf16 v[112:115], v[178:181], v[186:189], v[112:115]
	v_mfma_f32_16x16x32_bf16 v[100:103], v[170:173], v[194:197], v[100:103]
	v_mfma_f32_16x16x32_bf16 v[96:99], v[178:181], v[194:197], v[96:99]
	v_mfma_f32_16x16x32_bf16 v[84:87], v[170:173], v[224:227], v[84:87]
	v_mfma_f32_16x16x32_bf16 v[80:83], v[178:181], v[224:227], v[80:83]
	v_mfma_f32_16x16x32_bf16 v[68:71], v[170:173], v[232:235], v[68:71]
	v_mfma_f32_16x16x32_bf16 v[64:67], v[178:181], v[232:235], v[64:67]
	v_mfma_f32_16x16x32_bf16 v[116:119], v[174:177], v[190:193], v[116:119]
	v_mfma_f32_16x16x32_bf16 v[112:115], v[182:185], v[190:193], v[112:115]
	v_mfma_f32_16x16x32_bf16 v[100:103], v[174:177], v[220:223], v[100:103]
	v_mfma_f32_16x16x32_bf16 v[96:99], v[182:185], v[220:223], v[96:99]
	v_mfma_f32_16x16x32_bf16 v[84:87], v[174:177], v[228:231], v[84:87]
	v_mfma_f32_16x16x32_bf16 v[80:83], v[182:185], v[228:231], v[80:83]
	v_mfma_f32_16x16x32_bf16 v[68:71], v[174:177], v[236:239], v[68:71]
	v_mfma_f32_16x16x32_bf16 v[64:67], v[182:185], v[236:239], v[64:67]
	s_setprio 0
	s_barrier
	s_add_i32 s58, s58, s35
	v_lshl_add_u64 v[154:155], s[56:57], 0, v[128:129]
	s_mov_b32 m0, s58
	ds_read_b128 v[186:189], v157 offset:16384
	ds_read_b128 v[190:193], v157 offset:17408
	ds_read_b128 v[194:197], v157 offset:18432
	ds_read_b128 v[220:223], v157 offset:19456
	ds_read_b128 v[224:227], v157 offset:20480
	ds_read_b128 v[228:231], v157 offset:21504
	ds_read_b128 v[232:235], v157 offset:22528
	ds_read_b128 v[236:239], v157 offset:23552
	global_load_lds_dwordx4 v[154:155], off
	s_add_i32 m0, s58, 0x2000
	v_lshl_add_u64 v[198:199], s[56:57], 0, v[140:141]
	s_add_u32 s56, s56, s2
	s_addc_u32 s57, s57, s3
	s_add_i32 s55, s55, s35
	global_load_lds_dwordx4 v[198:199], off
	v_lshl_add_u64 v[208:209], s[56:57], 0, v[128:129]
	s_mov_b32 m0, s55
	v_lshl_add_u64 v[244:245], s[56:57], 0, v[140:141]
	global_load_lds_dwordx4 v[208:209], off
	s_add_i32 m0, s55, 0x2000
	v_lshl_add_u64 v[246:247], s[26:27], 0, v[144:145]
	global_load_lds_dwordx4 v[244:245], off
	s_mov_b32 m0, s38
	v_lshl_add_u64 v[248:249], s[26:27], 0, v[142:143]
	global_load_lds_dwordx4 v[246:247], off
	s_mov_b32 m0, s39
	s_nop 0
	global_load_lds_dwordx4 v[248:249], off
	s_waitcnt vmcnt(8)
	s_waitcnt lgkmcnt(0)
	s_barrier
	s_setprio 1
	s_waitcnt lgkmcnt(0)
	v_mfma_f32_16x16x32_bf16 v[60:63], v[150:153], v[186:189], v[60:63]
	v_mfma_f32_16x16x32_bf16 v[56:59], v[162:165], v[186:189], v[56:59]
	v_mfma_f32_16x16x32_bf16 v[44:47], v[150:153], v[194:197], v[44:47]
	v_mfma_f32_16x16x32_bf16 v[40:43], v[162:165], v[194:197], v[40:43]
	v_mfma_f32_16x16x32_bf16 v[28:31], v[150:153], v[224:227], v[28:31]
	v_mfma_f32_16x16x32_bf16 v[24:27], v[162:165], v[224:227], v[24:27]
	v_mfma_f32_16x16x32_bf16 v[12:15], v[150:153], v[232:235], v[12:15]
	v_mfma_f32_16x16x32_bf16 v[8:11], v[162:165], v[232:235], v[8:11]
	v_mfma_f32_16x16x32_bf16 v[60:63], v[158:161], v[190:193], v[60:63]
	v_mfma_f32_16x16x32_bf16 v[56:59], v[166:169], v[190:193], v[56:59]
	v_mfma_f32_16x16x32_bf16 v[44:47], v[158:161], v[220:223], v[44:47]
	v_mfma_f32_16x16x32_bf16 v[40:43], v[166:169], v[220:223], v[40:43]
	v_mfma_f32_16x16x32_bf16 v[28:31], v[158:161], v[228:231], v[28:31]
	v_mfma_f32_16x16x32_bf16 v[24:27], v[166:169], v[228:231], v[24:27]
	v_mfma_f32_16x16x32_bf16 v[12:15], v[158:161], v[236:239], v[12:15]
	v_mfma_f32_16x16x32_bf16 v[8:11], v[166:169], v[236:239], v[8:11]
	s_setprio 0
	s_setprio 1
	v_mfma_f32_16x16x32_bf16 v[52:55], v[170:173], v[186:189], v[52:55]
	v_mfma_f32_16x16x32_bf16 v[48:51], v[178:181], v[186:189], v[48:51]
	v_mfma_f32_16x16x32_bf16 v[36:39], v[170:173], v[194:197], v[36:39]
	v_mfma_f32_16x16x32_bf16 v[32:35], v[178:181], v[194:197], v[32:35]
	v_mfma_f32_16x16x32_bf16 v[20:23], v[170:173], v[224:227], v[20:23]
	v_mfma_f32_16x16x32_bf16 v[16:19], v[178:181], v[224:227], v[16:19]
	v_mfma_f32_16x16x32_bf16 v[4:7], v[170:173], v[232:235], v[4:7]
	v_mfma_f32_16x16x32_bf16 v[0:3], v[178:181], v[232:235], v[0:3]
	v_mfma_f32_16x16x32_bf16 v[52:55], v[174:177], v[190:193], v[52:55]
	v_mfma_f32_16x16x32_bf16 v[48:51], v[182:185], v[190:193], v[48:51]
	v_mfma_f32_16x16x32_bf16 v[36:39], v[174:177], v[220:223], v[36:39]
	v_mfma_f32_16x16x32_bf16 v[32:35], v[182:185], v[220:223], v[32:35]
	v_mfma_f32_16x16x32_bf16 v[20:23], v[174:177], v[228:231], v[20:23]
	v_mfma_f32_16x16x32_bf16 v[16:19], v[182:185], v[228:231], v[16:19]
	v_mfma_f32_16x16x32_bf16 v[4:7], v[174:177], v[236:239], v[4:7]
	v_mfma_f32_16x16x32_bf16 v[0:3], v[182:185], v[236:239], v[0:3]
	s_setprio 0
	s_barrier
	s_add_i32 s55, 16, 0x18000
	s_add_i32 s56, 16, 0x1c000
	v_add_u32_e32 v166, s55, v137
	v_add_u32_e32 v182, s56, v137
	ds_read_b128 v[150:153], v166
	ds_read_b128 v[158:161], v166 offset:1024
	ds_read_b128 v[162:165], v166 offset:2048
	ds_read_b128 v[166:169], v166 offset:3072
	ds_read_b128 v[170:173], v182
	ds_read_b128 v[174:177], v182 offset:1024
	ds_read_b128 v[178:181], v182 offset:2048
	ds_read_b128 v[182:185], v182 offset:3072
	s_add_u32 s26, s26, s2
	s_addc_u32 s27, s27, s3
	s_mov_b32 m0, s42
	v_lshl_add_u64 v[250:251], s[26:27], 0, v[144:145]
	ds_read_b128 v[186:189], v157 offset:32768
	ds_read_b128 v[190:193], v157 offset:33792
	ds_read_b128 v[194:197], v157 offset:34816
	ds_read_b128 v[220:223], v157 offset:35840
	ds_read_b128 v[224:227], v157 offset:36864
	ds_read_b128 v[228:231], v157 offset:37888
	ds_read_b128 v[232:235], v157 offset:38912
	ds_read_b128 v[236:239], v157 offset:39936
	global_load_lds_dwordx4 v[250:251], off
	v_lshl_add_u64 v[250:251], s[26:27], 0, v[142:143]
	s_mov_b32 m0, s43
	s_nop 0
	global_load_lds_dwordx4 v[250:251], off
	s_waitcnt vmcnt(8)
	s_waitcnt lgkmcnt(0)
	s_barrier
	s_setprio 1
	s_waitcnt lgkmcnt(0)
	v_mfma_f32_16x16x32_bf16 v[120:123], v[150:153], v[186:189], v[120:123]
	v_mfma_f32_16x16x32_bf16 v[124:127], v[162:165], v[186:189], v[124:127]
	v_mfma_f32_16x16x32_bf16 v[108:111], v[150:153], v[194:197], v[108:111]
	v_mfma_f32_16x16x32_bf16 v[104:107], v[162:165], v[194:197], v[104:107]
	v_mfma_f32_16x16x32_bf16 v[92:95], v[150:153], v[224:227], v[92:95]
	v_mfma_f32_16x16x32_bf16 v[88:91], v[162:165], v[224:227], v[88:91]
	v_mfma_f32_16x16x32_bf16 v[76:79], v[150:153], v[232:235], v[76:79]
	v_mfma_f32_16x16x32_bf16 v[72:75], v[162:165], v[232:235], v[72:75]
	v_mfma_f32_16x16x32_bf16 v[120:123], v[158:161], v[190:193], v[120:123]
	v_mfma_f32_16x16x32_bf16 v[124:127], v[166:169], v[190:193], v[124:127]
	v_mfma_f32_16x16x32_bf16 v[108:111], v[158:161], v[220:223], v[108:111]
	v_mfma_f32_16x16x32_bf16 v[104:107], v[166:169], v[220:223], v[104:107]
	v_mfma_f32_16x16x32_bf16 v[92:95], v[158:161], v[228:231], v[92:95]
	v_mfma_f32_16x16x32_bf16 v[88:91], v[166:169], v[228:231], v[88:91]
	v_mfma_f32_16x16x32_bf16 v[76:79], v[158:161], v[236:239], v[76:79]
	v_mfma_f32_16x16x32_bf16 v[72:75], v[166:169], v[236:239], v[72:75]
	s_setprio 0
	s_setprio 1
	v_mfma_f32_16x16x32_bf16 v[116:119], v[170:173], v[186:189], v[116:119]
	v_mfma_f32_16x16x32_bf16 v[112:115], v[178:181], v[186:189], v[112:115]
	v_mfma_f32_16x16x32_bf16 v[100:103], v[170:173], v[194:197], v[100:103]
	v_mfma_f32_16x16x32_bf16 v[96:99], v[178:181], v[194:197], v[96:99]
	v_mfma_f32_16x16x32_bf16 v[84:87], v[170:173], v[224:227], v[84:87]
	v_mfma_f32_16x16x32_bf16 v[80:83], v[178:181], v[224:227], v[80:83]
	v_mfma_f32_16x16x32_bf16 v[68:71], v[170:173], v[232:235], v[68:71]
	v_mfma_f32_16x16x32_bf16 v[64:67], v[178:181], v[232:235], v[64:67]
	v_mfma_f32_16x16x32_bf16 v[116:119], v[174:177], v[190:193], v[116:119]
	v_mfma_f32_16x16x32_bf16 v[112:115], v[182:185], v[190:193], v[112:115]
	v_mfma_f32_16x16x32_bf16 v[100:103], v[174:177], v[220:223], v[100:103]
	v_mfma_f32_16x16x32_bf16 v[96:99], v[182:185], v[220:223], v[96:99]
	v_mfma_f32_16x16x32_bf16 v[84:87], v[174:177], v[228:231], v[84:87]
	v_mfma_f32_16x16x32_bf16 v[80:83], v[182:185], v[228:231], v[80:83]
	v_mfma_f32_16x16x32_bf16 v[68:71], v[174:177], v[236:239], v[68:71]
	v_mfma_f32_16x16x32_bf16 v[64:67], v[182:185], v[236:239], v[64:67]
	s_setprio 0
	s_barrier
	s_add_i32 s26, s55, s35
	v_lshl_add_u64 v[154:155], v[154:155], 0, s[98:99]
	s_mov_b32 m0, s26
	ds_read_b128 v[186:189], v157 offset:49152
	ds_read_b128 v[190:193], v157 offset:50176
	ds_read_b128 v[194:197], v157 offset:51200
	ds_read_b128 v[220:223], v157 offset:52224
	ds_read_b128 v[224:227], v157 offset:53248
	ds_read_b128 v[228:231], v157 offset:54272
	ds_read_b128 v[232:235], v157 offset:55296
	ds_read_b128 v[236:239], v157 offset:56320
	global_load_lds_dwordx4 v[154:155], off
	v_lshl_add_u64 v[154:155], v[198:199], 0, s[98:99]
	s_add_i32 m0, s26, 0x2000
	s_add_i32 s26, s56, s35
	global_load_lds_dwordx4 v[154:155], off
	v_lshl_add_u64 v[154:155], v[208:209], 0, s[98:99]
	s_mov_b32 m0, s26
	s_nop 0
	global_load_lds_dwordx4 v[154:155], off
	v_lshl_add_u64 v[154:155], v[244:245], 0, s[98:99]
	s_add_i32 m0, s26, 0x2000
	s_nop 0
	global_load_lds_dwordx4 v[154:155], off
	v_lshl_add_u64 v[154:155], v[246:247], 0, s[98:99]
	s_mov_b32 m0, s44
	s_nop 0
	global_load_lds_dwordx4 v[154:155], off
	v_lshl_add_u64 v[154:155], v[248:249], 0, s[98:99]
	s_mov_b32 m0, s45
	s_nop 0
	global_load_lds_dwordx4 v[154:155], off
	s_waitcnt vmcnt(8)
	s_waitcnt lgkmcnt(0)
	s_barrier
	s_setprio 1
	s_waitcnt lgkmcnt(0)
	v_mfma_f32_16x16x32_bf16 v[60:63], v[150:153], v[186:189], v[60:63]
	v_mfma_f32_16x16x32_bf16 v[56:59], v[162:165], v[186:189], v[56:59]
	v_mfma_f32_16x16x32_bf16 v[44:47], v[150:153], v[194:197], v[44:47]
	v_mfma_f32_16x16x32_bf16 v[40:43], v[162:165], v[194:197], v[40:43]
	v_mfma_f32_16x16x32_bf16 v[28:31], v[150:153], v[224:227], v[28:31]
	v_mfma_f32_16x16x32_bf16 v[24:27], v[162:165], v[224:227], v[24:27]
	v_mfma_f32_16x16x32_bf16 v[12:15], v[150:153], v[232:235], v[12:15]
	v_mfma_f32_16x16x32_bf16 v[8:11], v[162:165], v[232:235], v[8:11]
	v_mfma_f32_16x16x32_bf16 v[60:63], v[158:161], v[190:193], v[60:63]
	v_mfma_f32_16x16x32_bf16 v[56:59], v[166:169], v[190:193], v[56:59]
	v_mfma_f32_16x16x32_bf16 v[44:47], v[158:161], v[220:223], v[44:47]
	v_mfma_f32_16x16x32_bf16 v[40:43], v[166:169], v[220:223], v[40:43]
	v_mfma_f32_16x16x32_bf16 v[28:31], v[158:161], v[228:231], v[28:31]
	v_mfma_f32_16x16x32_bf16 v[24:27], v[166:169], v[228:231], v[24:27]
	v_mfma_f32_16x16x32_bf16 v[12:15], v[158:161], v[236:239], v[12:15]
	v_mfma_f32_16x16x32_bf16 v[8:11], v[166:169], v[236:239], v[8:11]
	s_setprio 0
	s_setprio 1
	v_mfma_f32_16x16x32_bf16 v[52:55], v[170:173], v[186:189], v[52:55]
	v_mfma_f32_16x16x32_bf16 v[48:51], v[178:181], v[186:189], v[48:51]
	v_mfma_f32_16x16x32_bf16 v[36:39], v[170:173], v[194:197], v[36:39]
	v_mfma_f32_16x16x32_bf16 v[32:35], v[178:181], v[194:197], v[32:35]
	v_mfma_f32_16x16x32_bf16 v[20:23], v[170:173], v[224:227], v[20:23]
	v_mfma_f32_16x16x32_bf16 v[16:19], v[178:181], v[224:227], v[16:19]
	v_mfma_f32_16x16x32_bf16 v[4:7], v[170:173], v[232:235], v[4:7]
	v_mfma_f32_16x16x32_bf16 v[0:3], v[178:181], v[232:235], v[0:3]
	v_mfma_f32_16x16x32_bf16 v[52:55], v[174:177], v[190:193], v[52:55]
	v_mfma_f32_16x16x32_bf16 v[48:51], v[182:185], v[190:193], v[48:51]
	v_mfma_f32_16x16x32_bf16 v[36:39], v[174:177], v[220:223], v[36:39]
	v_mfma_f32_16x16x32_bf16 v[32:35], v[182:185], v[220:223], v[32:35]
	v_mfma_f32_16x16x32_bf16 v[20:23], v[174:177], v[228:231], v[20:23]
	v_mfma_f32_16x16x32_bf16 v[16:19], v[182:185], v[228:231], v[16:19]
	v_mfma_f32_16x16x32_bf16 v[4:7], v[174:177], v[236:239], v[4:7]
	v_mfma_f32_16x16x32_bf16 v[0:3], v[182:185], v[236:239], v[0:3]
	s_setprio 0
	s_add_u32 s0, s0, 0x100
	s_addc_u32 s1, s1, 0
	s_add_u32 s28, s28, 0x100
	s_addc_u32 s29, s29, 0
	s_cmp_ge_i32 s54, s46
	s_mov_b32 s26, s54
	s_barrier
	s_cbranch_scc0 .LBB0_139
	v_readlane_b32 s58, v255, 20
	v_readlane_b32 s59, v255, 21

.LBB0_339:
	s_add_i32 s54, s26, 2
	s_add_u32 s55, s0, 0x80
	s_addc_u32 s27, s1, 0
	s_add_i32 s58, 16, 0x10000
	s_cmp_eq_u32 s47, s26
	s_cselect_b32 s27, s21, s27
	s_cselect_b32 s26, s20, s55
	s_cselect_b32 s57, s25, s29
	s_cselect_b32 s56, s24, s28
	s_add_i32 s55, 16, 0x14000
	v_add_u32_e32 v164, s58, v137
	v_add_u32_e32 v180, s55, v137
	ds_read_b128 v[150:153], v164
	ds_read_b128 v[156:159], v164 offset:1024
	ds_read_b128 v[160:163], v164 offset:2048
	ds_read_b128 v[164:167], v164 offset:3072
	ds_read_b128 v[168:171], v180
	ds_read_b128 v[172:175], v180 offset:1024
	ds_read_b128 v[176:179], v180 offset:2048
	ds_read_b128 v[180:183], v180 offset:3072
	v_lshl_add_u64 v[236:237], s[0:1], 0, v[146:147]
	s_add_i32 m0, s37, 0xc000
	ds_read_b128 v[184:187], v155
	ds_read_b128 v[188:191], v155 offset:1024
	ds_read_b128 v[192:195], v155 offset:2048
	ds_read_b128 v[196:199], v155 offset:3072
	ds_read_b128 v[220:223], v155 offset:4096
	ds_read_b128 v[224:227], v155 offset:5120
	ds_read_b128 v[228:231], v155 offset:6144
	ds_read_b128 v[232:235], v155 offset:7168
	global_load_lds_dwordx4 v[236:237], off
	v_lshl_add_u64 v[236:237], s[0:1], 0, v[148:149]
	s_add_i32 m0, s37, 0xe000
	s_nop 0
	global_load_lds_dwordx4 v[236:237], off
	s_waitcnt vmcnt(8)
	s_waitcnt lgkmcnt(0)
	s_barrier
	s_setprio 1
	s_waitcnt lgkmcnt(0)
	v_mfma_f32_16x16x32_bf16 v[120:123], v[150:153], v[184:187], v[120:123]
	v_mfma_f32_16x16x32_bf16 v[124:127], v[160:163], v[184:187], v[124:127]
	v_mfma_f32_16x16x32_bf16 v[108:111], v[150:153], v[192:195], v[108:111]
	v_mfma_f32_16x16x32_bf16 v[104:107], v[160:163], v[192:195], v[104:107]
	v_mfma_f32_16x16x32_bf16 v[92:95], v[150:153], v[220:223], v[92:95]
	v_mfma_f32_16x16x32_bf16 v[88:91], v[160:163], v[220:223], v[88:91]
	v_mfma_f32_16x16x32_bf16 v[76:79], v[150:153], v[228:231], v[76:79]
	v_mfma_f32_16x16x32_bf16 v[72:75], v[160:163], v[228:231], v[72:75]
	v_mfma_f32_16x16x32_bf16 v[120:123], v[156:159], v[188:191], v[120:123]
	v_mfma_f32_16x16x32_bf16 v[124:127], v[164:167], v[188:191], v[124:127]
	v_mfma_f32_16x16x32_bf16 v[108:111], v[156:159], v[196:199], v[108:111]
	v_mfma_f32_16x16x32_bf16 v[104:107], v[164:167], v[196:199], v[104:107]
	v_mfma_f32_16x16x32_bf16 v[92:95], v[156:159], v[224:227], v[92:95]
	v_mfma_f32_16x16x32_bf16 v[88:91], v[164:167], v[224:227], v[88:91]
	v_mfma_f32_16x16x32_bf16 v[76:79], v[156:159], v[232:235], v[76:79]
	v_mfma_f32_16x16x32_bf16 v[72:75], v[164:167], v[232:235], v[72:75]
	s_setprio 0
	s_setprio 1
	v_mfma_f32_16x16x32_bf16 v[116:119], v[168:171], v[184:187], v[116:119]
	v_mfma_f32_16x16x32_bf16 v[112:115], v[176:179], v[184:187], v[112:115]
	v_mfma_f32_16x16x32_bf16 v[100:103], v[168:171], v[192:195], v[100:103]
	v_mfma_f32_16x16x32_bf16 v[96:99], v[176:179], v[192:195], v[96:99]
	v_mfma_f32_16x16x32_bf16 v[84:87], v[168:171], v[220:223], v[84:87]
	v_mfma_f32_16x16x32_bf16 v[80:83], v[176:179], v[220:223], v[80:83]
	v_mfma_f32_16x16x32_bf16 v[68:71], v[168:171], v[228:231], v[68:71]
	v_mfma_f32_16x16x32_bf16 v[64:67], v[176:179], v[228:231], v[64:67]
	v_mfma_f32_16x16x32_bf16 v[116:119], v[172:175], v[188:191], v[116:119]
	v_mfma_f32_16x16x32_bf16 v[112:115], v[180:183], v[188:191], v[112:115]
	v_mfma_f32_16x16x32_bf16 v[100:103], v[172:175], v[196:199], v[100:103]
	v_mfma_f32_16x16x32_bf16 v[96:99], v[180:183], v[196:199], v[96:99]
	v_mfma_f32_16x16x32_bf16 v[84:87], v[172:175], v[224:227], v[84:87]
	v_mfma_f32_16x16x32_bf16 v[80:83], v[180:183], v[224:227], v[80:83]
	v_mfma_f32_16x16x32_bf16 v[68:71], v[172:175], v[232:235], v[68:71]
	v_mfma_f32_16x16x32_bf16 v[64:67], v[180:183], v[232:235], v[64:67]
	s_setprio 0
	s_barrier
	s_add_i32 s58, s58, s34
	v_lshl_add_u64 v[236:237], s[56:57], 0, v[128:129]
	s_mov_b32 m0, s58
	ds_read_b128 v[184:187], v155 offset:16384
	ds_read_b128 v[188:191], v155 offset:17408
	ds_read_b128 v[192:195], v155 offset:18432
	ds_read_b128 v[196:199], v155 offset:19456
	ds_read_b128 v[220:223], v155 offset:20480
	ds_read_b128 v[224:227], v155 offset:21504
	ds_read_b128 v[228:231], v155 offset:22528
	ds_read_b128 v[232:235], v155 offset:23552
	global_load_lds_dwordx4 v[236:237], off
	s_add_i32 m0, s58, 0x2000
	v_lshl_add_u64 v[238:239], s[56:57], 0, v[140:141]
	s_add_u32 s56, s56, s2
	s_addc_u32 s57, s57, s3
	s_add_i32 s55, s55, s34
	global_load_lds_dwordx4 v[238:239], off
	v_lshl_add_u64 v[244:245], s[56:57], 0, v[128:129]
	s_mov_b32 m0, s55
	v_lshl_add_u64 v[246:247], s[56:57], 0, v[140:141]
	global_load_lds_dwordx4 v[244:245], off
	s_add_i32 m0, s55, 0x2000
	v_lshl_add_u64 v[248:249], s[26:27], 0, v[144:145]
	global_load_lds_dwordx4 v[246:247], off
	s_mov_b32 m0, s37
	v_lshl_add_u64 v[250:251], s[26:27], 0, v[142:143]
	global_load_lds_dwordx4 v[248:249], off
	s_mov_b32 m0, s38
	s_nop 0
	global_load_lds_dwordx4 v[250:251], off
	s_waitcnt vmcnt(8)
	s_waitcnt lgkmcnt(0)
	s_barrier
	s_setprio 1
	s_waitcnt lgkmcnt(0)
	v_mfma_f32_16x16x32_bf16 v[60:63], v[150:153], v[184:187], v[60:63]
	v_mfma_f32_16x16x32_bf16 v[56:59], v[160:163], v[184:187], v[56:59]
	v_mfma_f32_16x16x32_bf16 v[44:47], v[150:153], v[192:195], v[44:47]
	v_mfma_f32_16x16x32_bf16 v[40:43], v[160:163], v[192:195], v[40:43]
	v_mfma_f32_16x16x32_bf16 v[28:31], v[150:153], v[220:223], v[28:31]
	v_mfma_f32_16x16x32_bf16 v[24:27], v[160:163], v[220:223], v[24:27]
	v_mfma_f32_16x16x32_bf16 v[12:15], v[150:153], v[228:231], v[12:15]
	v_mfma_f32_16x16x32_bf16 v[8:11], v[160:163], v[228:231], v[8:11]
	v_mfma_f32_16x16x32_bf16 v[60:63], v[156:159], v[188:191], v[60:63]
	v_mfma_f32_16x16x32_bf16 v[56:59], v[164:167], v[188:191], v[56:59]
	v_mfma_f32_16x16x32_bf16 v[44:47], v[156:159], v[196:199], v[44:47]
	v_mfma_f32_16x16x32_bf16 v[40:43], v[164:167], v[196:199], v[40:43]
	v_mfma_f32_16x16x32_bf16 v[28:31], v[156:159], v[224:227], v[28:31]
	v_mfma_f32_16x16x32_bf16 v[24:27], v[164:167], v[224:227], v[24:27]
	v_mfma_f32_16x16x32_bf16 v[12:15], v[156:159], v[232:235], v[12:15]
	v_mfma_f32_16x16x32_bf16 v[8:11], v[164:167], v[232:235], v[8:11]
	s_setprio 0
	s_setprio 1
	v_mfma_f32_16x16x32_bf16 v[52:55], v[168:171], v[184:187], v[52:55]
	v_mfma_f32_16x16x32_bf16 v[48:51], v[176:179], v[184:187], v[48:51]
	v_mfma_f32_16x16x32_bf16 v[36:39], v[168:171], v[192:195], v[36:39]
	v_mfma_f32_16x16x32_bf16 v[32:35], v[176:179], v[192:195], v[32:35]
	v_mfma_f32_16x16x32_bf16 v[20:23], v[168:171], v[220:223], v[20:23]
	v_mfma_f32_16x16x32_bf16 v[16:19], v[176:179], v[220:223], v[16:19]
	v_mfma_f32_16x16x32_bf16 v[4:7], v[168:171], v[228:231], v[4:7]
	v_mfma_f32_16x16x32_bf16 v[0:3], v[176:179], v[228:231], v[0:3]
	v_mfma_f32_16x16x32_bf16 v[52:55], v[172:175], v[188:191], v[52:55]
	v_mfma_f32_16x16x32_bf16 v[48:51], v[180:183], v[188:191], v[48:51]
	v_mfma_f32_16x16x32_bf16 v[36:39], v[172:175], v[196:199], v[36:39]
	v_mfma_f32_16x16x32_bf16 v[32:35], v[180:183], v[196:199], v[32:35]
	v_mfma_f32_16x16x32_bf16 v[20:23], v[172:175], v[224:227], v[20:23]
	v_mfma_f32_16x16x32_bf16 v[16:19], v[180:183], v[224:227], v[16:19]
	v_mfma_f32_16x16x32_bf16 v[4:7], v[172:175], v[232:235], v[4:7]
	v_mfma_f32_16x16x32_bf16 v[0:3], v[180:183], v[232:235], v[0:3]
	s_setprio 0
	s_barrier
	s_add_i32 s55, 16, 0x18000
	s_add_i32 s56, 16, 0x1c000
	v_add_u32_e32 v164, s55, v137
	v_add_u32_e32 v180, s56, v137
	ds_read_b128 v[150:153], v164
	ds_read_b128 v[156:159], v164 offset:1024
	ds_read_b128 v[160:163], v164 offset:2048
	ds_read_b128 v[164:167], v164 offset:3072
	ds_read_b128 v[168:171], v180
	ds_read_b128 v[172:175], v180 offset:1024
	ds_read_b128 v[176:179], v180 offset:2048
	ds_read_b128 v[180:183], v180 offset:3072
	s_add_u32 s26, s26, s2
	s_addc_u32 s27, s27, s3
	s_mov_b32 m0, s39
	v_lshl_add_u64 v[208:209], s[26:27], 0, v[144:145]
	ds_read_b128 v[184:187], v155 offset:32768
	ds_read_b128 v[188:191], v155 offset:33792
	ds_read_b128 v[192:195], v155 offset:34816
	ds_read_b128 v[196:199], v155 offset:35840
	ds_read_b128 v[220:223], v155 offset:36864
	ds_read_b128 v[224:227], v155 offset:37888
	ds_read_b128 v[228:231], v155 offset:38912
	ds_read_b128 v[232:235], v155 offset:39936
	global_load_lds_dwordx4 v[208:209], off
	v_lshl_add_u64 v[208:209], s[26:27], 0, v[142:143]
	s_mov_b32 m0, s42
	s_nop 0
	global_load_lds_dwordx4 v[208:209], off
	s_waitcnt vmcnt(8)
	s_waitcnt lgkmcnt(0)
	s_barrier
	s_setprio 1
	s_waitcnt lgkmcnt(0)
	v_mfma_f32_16x16x32_bf16 v[120:123], v[150:153], v[184:187], v[120:123]
	v_mfma_f32_16x16x32_bf16 v[124:127], v[160:163], v[184:187], v[124:127]
	v_mfma_f32_16x16x32_bf16 v[108:111], v[150:153], v[192:195], v[108:111]
	v_mfma_f32_16x16x32_bf16 v[104:107], v[160:163], v[192:195], v[104:107]
	v_mfma_f32_16x16x32_bf16 v[92:95], v[150:153], v[220:223], v[92:95]
	v_mfma_f32_16x16x32_bf16 v[88:91], v[160:163], v[220:223], v[88:91]
	v_mfma_f32_16x16x32_bf16 v[76:79], v[150:153], v[228:231], v[76:79]
	v_mfma_f32_16x16x32_bf16 v[72:75], v[160:163], v[228:231], v[72:75]
	v_mfma_f32_16x16x32_bf16 v[120:123], v[156:159], v[188:191], v[120:123]
	v_mfma_f32_16x16x32_bf16 v[124:127], v[164:167], v[188:191], v[124:127]
	v_mfma_f32_16x16x32_bf16 v[108:111], v[156:159], v[196:199], v[108:111]
	v_mfma_f32_16x16x32_bf16 v[104:107], v[164:167], v[196:199], v[104:107]
	v_mfma_f32_16x16x32_bf16 v[92:95], v[156:159], v[224:227], v[92:95]
	v_mfma_f32_16x16x32_bf16 v[88:91], v[164:167], v[224:227], v[88:91]
	v_mfma_f32_16x16x32_bf16 v[76:79], v[156:159], v[232:235], v[76:79]
	v_mfma_f32_16x16x32_bf16 v[72:75], v[164:167], v[232:235], v[72:75]
	s_setprio 0
	s_setprio 1
	v_mfma_f32_16x16x32_bf16 v[116:119], v[168:171], v[184:187], v[116:119]
	v_mfma_f32_16x16x32_bf16 v[112:115], v[176:179], v[184:187], v[112:115]
	v_mfma_f32_16x16x32_bf16 v[100:103], v[168:171], v[192:195], v[100:103]
	v_mfma_f32_16x16x32_bf16 v[96:99], v[176:179], v[192:195], v[96:99]
	v_mfma_f32_16x16x32_bf16 v[84:87], v[168:171], v[220:223], v[84:87]
	v_mfma_f32_16x16x32_bf16 v[80:83], v[176:179], v[220:223], v[80:83]
	v_mfma_f32_16x16x32_bf16 v[68:71], v[168:171], v[228:231], v[68:71]
	v_mfma_f32_16x16x32_bf16 v[64:67], v[176:179], v[228:231], v[64:67]
	v_mfma_f32_16x16x32_bf16 v[116:119], v[172:175], v[188:191], v[116:119]
	v_mfma_f32_16x16x32_bf16 v[112:115], v[180:183], v[188:191], v[112:115]
	v_mfma_f32_16x16x32_bf16 v[100:103], v[172:175], v[196:199], v[100:103]
	v_mfma_f32_16x16x32_bf16 v[96:99], v[180:183], v[196:199], v[96:99]
	v_mfma_f32_16x16x32_bf16 v[84:87], v[172:175], v[224:227], v[84:87]
	v_mfma_f32_16x16x32_bf16 v[80:83], v[180:183], v[224:227], v[80:83]
	v_mfma_f32_16x16x32_bf16 v[68:71], v[172:175], v[232:235], v[68:71]
	v_mfma_f32_16x16x32_bf16 v[64:67], v[180:183], v[232:235], v[64:67]
	s_setprio 0
	s_barrier
	s_add_i32 s26, s55, s34
	v_lshl_add_u64 v[208:209], v[236:237], 0, s[98:99]
	s_mov_b32 m0, s26
	ds_read_b128 v[184:187], v155 offset:49152
	ds_read_b128 v[188:191], v155 offset:50176
	ds_read_b128 v[192:195], v155 offset:51200
	ds_read_b128 v[196:199], v155 offset:52224
	ds_read_b128 v[220:223], v155 offset:53248
	ds_read_b128 v[224:227], v155 offset:54272
	ds_read_b128 v[228:231], v155 offset:55296
	ds_read_b128 v[232:235], v155 offset:56320
	global_load_lds_dwordx4 v[208:209], off
	v_lshl_add_u64 v[208:209], v[238:239], 0, s[98:99]
	s_add_i32 m0, s26, 0x2000
	s_add_i32 s26, s56, s34
	global_load_lds_dwordx4 v[208:209], off
	v_lshl_add_u64 v[208:209], v[244:245], 0, s[98:99]
	s_mov_b32 m0, s26
	s_nop 0
	global_load_lds_dwordx4 v[208:209], off
	v_lshl_add_u64 v[208:209], v[246:247], 0, s[98:99]
	s_add_i32 m0, s26, 0x2000
	s_nop 0
	global_load_lds_dwordx4 v[208:209], off
	v_lshl_add_u64 v[208:209], v[248:249], 0, s[98:99]
	s_mov_b32 m0, s44
	s_nop 0
	global_load_lds_dwordx4 v[208:209], off
	v_lshl_add_u64 v[208:209], v[250:251], 0, s[98:99]
	s_mov_b32 m0, s45
	s_nop 0
	global_load_lds_dwordx4 v[208:209], off
	s_waitcnt vmcnt(8)
	s_waitcnt lgkmcnt(0)
	s_barrier
	s_setprio 1
	s_waitcnt lgkmcnt(0)
	v_mfma_f32_16x16x32_bf16 v[60:63], v[150:153], v[184:187], v[60:63]
	v_mfma_f32_16x16x32_bf16 v[56:59], v[160:163], v[184:187], v[56:59]
	v_mfma_f32_16x16x32_bf16 v[44:47], v[150:153], v[192:195], v[44:47]
	v_mfma_f32_16x16x32_bf16 v[40:43], v[160:163], v[192:195], v[40:43]
	v_mfma_f32_16x16x32_bf16 v[28:31], v[150:153], v[220:223], v[28:31]
	v_mfma_f32_16x16x32_bf16 v[24:27], v[160:163], v[220:223], v[24:27]
	v_mfma_f32_16x16x32_bf16 v[12:15], v[150:153], v[228:231], v[12:15]
	v_mfma_f32_16x16x32_bf16 v[8:11], v[160:163], v[228:231], v[8:11]
	v_mfma_f32_16x16x32_bf16 v[60:63], v[156:159], v[188:191], v[60:63]
	v_mfma_f32_16x16x32_bf16 v[56:59], v[164:167], v[188:191], v[56:59]
	v_mfma_f32_16x16x32_bf16 v[44:47], v[156:159], v[196:199], v[44:47]
	v_mfma_f32_16x16x32_bf16 v[40:43], v[164:167], v[196:199], v[40:43]
	v_mfma_f32_16x16x32_bf16 v[28:31], v[156:159], v[224:227], v[28:31]
	v_mfma_f32_16x16x32_bf16 v[24:27], v[164:167], v[224:227], v[24:27]
	v_mfma_f32_16x16x32_bf16 v[12:15], v[156:159], v[232:235], v[12:15]
	v_mfma_f32_16x16x32_bf16 v[8:11], v[164:167], v[232:235], v[8:11]
	s_setprio 0
	s_setprio 1
	v_mfma_f32_16x16x32_bf16 v[52:55], v[168:171], v[184:187], v[52:55]
	v_mfma_f32_16x16x32_bf16 v[48:51], v[176:179], v[184:187], v[48:51]
	v_mfma_f32_16x16x32_bf16 v[36:39], v[168:171], v[192:195], v[36:39]
	v_mfma_f32_16x16x32_bf16 v[32:35], v[176:179], v[192:195], v[32:35]
	v_mfma_f32_16x16x32_bf16 v[20:23], v[168:171], v[220:223], v[20:23]
	v_mfma_f32_16x16x32_bf16 v[16:19], v[176:179], v[220:223], v[16:19]
	v_mfma_f32_16x16x32_bf16 v[4:7], v[168:171], v[228:231], v[4:7]
	v_mfma_f32_16x16x32_bf16 v[0:3], v[176:179], v[228:231], v[0:3]
	v_mfma_f32_16x16x32_bf16 v[52:55], v[172:175], v[188:191], v[52:55]
	v_mfma_f32_16x16x32_bf16 v[48:51], v[180:183], v[188:191], v[48:51]
	v_mfma_f32_16x16x32_bf16 v[36:39], v[172:175], v[196:199], v[36:39]
	v_mfma_f32_16x16x32_bf16 v[32:35], v[180:183], v[196:199], v[32:35]
	v_mfma_f32_16x16x32_bf16 v[20:23], v[172:175], v[224:227], v[20:23]
	v_mfma_f32_16x16x32_bf16 v[16:19], v[180:183], v[224:227], v[16:19]
	v_mfma_f32_16x16x32_bf16 v[4:7], v[172:175], v[232:235], v[4:7]
	v_mfma_f32_16x16x32_bf16 v[0:3], v[180:183], v[232:235], v[0:3]
	s_setprio 0
	s_add_u32 s0, s0, 0x100
	s_addc_u32 s1, s1, 0
	s_add_u32 s28, s28, 0x100
	s_addc_u32 s29, s29, 0
	s_cmp_ge_i32 s54, s46
	s_mov_b32 s26, s54
	s_barrier
	s_cbranch_scc0 .LBB0_339
	v_readlane_b32 s58, v255, 20
	v_readlane_b32 s59, v255, 21
